# hand-scheduled attention K/V loop body (groups half a tile apart, in-place P pack) with body priority 2, on the priority build
# speedup vs baseline: 1.0830x; 1.0076x over previous
.LBB0_452:
	s_setprio 2
	v_add3_u32 v197, s54, v190, v215
	ds_read_b128 v[68:71], v197
	ds_read_b128 v[72:75], v197 offset:32
	ds_read_b128 v[76:79], v197 offset:64
	ds_read_b128 v[80:83], v197 offset:96
	ds_read_b128 v[84:87], v197 offset:4608
	ds_read_b128 v[88:91], v197 offset:4640
	ds_read_b128 v[92:95], v197 offset:4672
	ds_read_b128 v[96:99], v197 offset:4704
	v_lshl_add_u64 v[136:137], v[198:199], 0, s[16:17]
	v_add_co_u32_e32 v138, vcc, 0xdee2000, v136
	s_nop 1
	v_addc_co_u32_e32 v139, vcc, 0, v137, vcc
	v_add_co_u32_e32 v140, vcc, 0xdee3000, v136
	s_nop 1
	v_addc_co_u32_e32 v141, vcc, 0, v137, vcc
	global_load_dwordx4 v[136:139], v[138:139], off
	s_nop 0
	global_load_dwordx4 v[140:143], v[140:141], off
	s_waitcnt lgkmcnt(7)
	v_mfma_f32_32x32x16_bf16 v[100:115], v[68:71], v[132:135], 0
	v_lshl_add_u64 v[66:67], v[200:201], 0, s[16:17]
	v_add_co_u32_e32 v144, vcc, 0xe3de000, v66
	s_waitcnt lgkmcnt(6)
	v_mfma_f32_32x32x16_bf16 v[100:115], v[72:75], v[156:159], v[100:115]
	s_nop 1
	v_addc_co_u32_e32 v145, vcc, 0, v67, vcc
	s_waitcnt lgkmcnt(5)
	v_mfma_f32_32x32x16_bf16 v[100:115], v[76:79], v[152:155], v[100:115]
	v_add_co_u32_e32 v66, vcc, 0xe422000, v66
	s_nop 1
	s_waitcnt lgkmcnt(4)
	v_mfma_f32_32x32x16_bf16 v[100:115], v[80:83], v[148:151], v[100:115]
	v_addc_co_u32_e32 v67, vcc, 0, v67, vcc
	global_load_dwordx4 v[176:179], v[144:145], off offset:256
	s_waitcnt lgkmcnt(3)
	v_mfma_f32_32x32x16_bf16 v[116:131], v[84:87], v[132:135], 0
	s_nop 0
	global_load_dwordx4 v[144:147], v[66:67], off offset:256
	s_waitcnt lgkmcnt(2)
	v_mfma_f32_32x32x16_bf16 v[116:131], v[88:91], v[156:159], v[116:131]
	v_add3_u32 v210, s54, v188, v65
	v_add_u32_e32 v211, 0x3000, v210
	s_waitcnt lgkmcnt(1)
	v_mfma_f32_32x32x16_bf16 v[116:131], v[92:95], v[152:155], v[116:131]
	v_add_u32_e32 v210, 0x2000, v210
	s_waitcnt lgkmcnt(0)
	v_mfma_f32_32x32x16_bf16 v[116:131], v[96:99], v[148:151], v[116:131]
	ds_read_b128 v[202:205], v197 offset:4608
	ds_read_b128 v[206:209], v197 offset:4640
	ds_read_b128 v[218:221], v197 offset:4672
	v_mfma_f32_32x32x16_bf16 v[84:99], v[68:71], v[172:175], 0
	v_max3_f32 v67, v100, v101, v102
	v_max3_f32 v67, v67, v103, v104
	v_mfma_f32_32x32x16_bf16 v[84:99], v[72:75], v[168:171], v[84:99]
	v_max3_f32 v67, v67, v105, v106
	v_max3_f32 v67, v67, v107, v108
	v_mfma_f32_32x32x16_bf16 v[84:99], v[76:79], v[164:167], v[84:99]
	v_max3_f32 v67, v67, v109, v110
	v_max3_f32 v67, v67, v111, v112
	v_mfma_f32_32x32x16_bf16 v[84:99], v[80:83], v[160:163], v[84:99]
	v_max3_f32 v67, v67, v113, v114
	v_max_f32_e32 v67, v67, v115
	s_waitcnt lgkmcnt(2)
	v_mfma_f32_32x32x16_bf16 v[68:83], v[202:205], v[172:175], 0
	ds_read_b128 v[202:205], v197 offset:4704
	v_max3_f32 v182, v116, v117, v118
	v_max3_f32 v182, v182, v119, v120
	v_max3_f32 v182, v182, v121, v122
	v_max3_f32 v182, v182, v123, v124
	s_waitcnt lgkmcnt(2)
	v_mfma_f32_32x32x16_bf16 v[68:83], v[206:209], v[168:171], v[68:83]
	v_max3_f32 v182, v182, v125, v126
	v_max3_f32 v182, v182, v127, v128
	v_max3_f32 v182, v182, v129, v130
	v_max_f32_e32 v182, v182, v131
	v_max_f32_e32 v67, v67, v182
	ds_bpermute_b32 v182, v191, v67
	s_waitcnt lgkmcnt(2)
	v_mfma_f32_32x32x16_bf16 v[68:83], v[218:221], v[164:167], v[68:83]
	s_waitcnt lgkmcnt(1)
	v_mfma_f32_32x32x16_bf16 v[68:83], v[202:205], v[160:163], v[68:83]
	ds_read2_b64 v[206:209], v210 offset0:128 offset1:130
	ds_read2_b64 v[218:221], v211 offset0:160 offset1:162
	s_waitcnt lgkmcnt(2)
	v_max3_f32 v66, v216, v67, v182
	v_cmp_gt_f32_e32 vcc, v66, v216
	s_cbranch_vccz .Lattn_keep0
	v_sub_f32_e32 v182, v216, v66
	v_exp_f32_e32 v182, v182
	s_nop 0
	v_pk_mul_f32 v[48:49], v[48:49], v[182:183] op_sel_hi:[1,0]
	v_pk_mul_f32 v[50:51], v[50:51], v[182:183] op_sel_hi:[1,0]
	v_pk_mul_f32 v[52:53], v[52:53], v[182:183] op_sel_hi:[1,0]
	v_pk_mul_f32 v[54:55], v[54:55], v[182:183] op_sel_hi:[1,0]
	v_pk_mul_f32 v[56:57], v[56:57], v[182:183] op_sel_hi:[1,0]
	v_pk_mul_f32 v[58:59], v[58:59], v[182:183] op_sel_hi:[1,0]
	v_pk_mul_f32 v[60:61], v[60:61], v[182:183] op_sel_hi:[1,0]
	v_pk_mul_f32 v[62:63], v[62:63], v[182:183] op_sel_hi:[1,0]
	v_pk_mul_f32 v[16:17], v[16:17], v[182:183] op_sel_hi:[1,0]
	v_pk_mul_f32 v[18:19], v[18:19], v[182:183] op_sel_hi:[1,0]
	v_pk_mul_f32 v[20:21], v[20:21], v[182:183] op_sel_hi:[1,0]
	v_pk_mul_f32 v[22:23], v[22:23], v[182:183] op_sel_hi:[1,0]
	v_pk_mul_f32 v[24:25], v[24:25], v[182:183] op_sel_hi:[1,0]
	v_pk_mul_f32 v[26:27], v[26:27], v[182:183] op_sel_hi:[1,0]
	v_pk_mul_f32 v[28:29], v[28:29], v[182:183] op_sel_hi:[1,0]
	v_pk_mul_f32 v[30:31], v[30:31], v[182:183] op_sel_hi:[1,0]
	v_mul_f32_e32 v194, v194, v182
.Lattn_keep0:
	v_sub_f32_e32 v100, v100, v66
	v_sub_f32_e32 v101, v101, v66
	v_exp_f32_e32 v100, v100
	v_sub_f32_e32 v102, v102, v66
	v_exp_f32_e32 v101, v101
	v_max3_f32 v67, v84, v85, v86
	v_add_f32_e32 v194, v194, v100
	v_sub_f32_e32 v103, v103, v66
	v_exp_f32_e32 v102, v102
	v_add_f32_e32 v194, v194, v101
	v_sub_f32_e32 v104, v104, v66
	v_max3_f32 v67, v67, v87, v88
	v_exp_f32_e32 v103, v103
	v_add_f32_e32 v194, v194, v102
	v_sub_f32_e32 v105, v105, v66
	v_exp_f32_e32 v104, v104
	v_add_f32_e32 v194, v194, v103
	v_max3_f32 v67, v67, v89, v90
	v_sub_f32_e32 v106, v106, v66
	v_exp_f32_e32 v105, v105
	v_add_f32_e32 v194, v194, v104
	v_sub_f32_e32 v107, v107, v66
	v_exp_f32_e32 v106, v106
	v_max3_f32 v67, v67, v91, v92
	v_add_f32_e32 v194, v194, v105
	v_sub_f32_e32 v108, v108, v66
	v_exp_f32_e32 v107, v107
	v_add_f32_e32 v194, v194, v106
	v_sub_f32_e32 v109, v109, v66
	v_max3_f32 v67, v67, v93, v94
	v_exp_f32_e32 v108, v108
	v_add_f32_e32 v194, v194, v107
	v_cvt_pk_bf16_f32 v100, v100, v101
	v_cvt_pk_bf16_f32 v101, v102, v103
	v_cvt_pk_bf16_f32 v102, v104, v105
	v_max3_f32 v67, v67, v95, v96
	v_cvt_pk_bf16_f32 v103, v106, v107
	ds_read2_b64 v[202:205], v210 offset0:132 offset1:134
	ds_read2_b64 v[104:107], v211 offset0:164 offset1:166
	v_sub_f32_e32 v110, v110, v66
	v_exp_f32_e32 v109, v109
	s_waitcnt lgkmcnt(3)
	v_mfma_f32_32x32x16_bf16 v[48:63], v[206:209], v[100:103], v[48:63]
	v_add_f32_e32 v194, v194, v108
	v_sub_f32_e32 v111, v111, v66
	v_max3_f32 v67, v67, v97, v98
	v_exp_f32_e32 v110, v110
	v_add_f32_e32 v194, v194, v109
	v_sub_f32_e32 v112, v112, v66
	v_exp_f32_e32 v111, v111
	v_add_f32_e32 v194, v194, v110
	v_max_f32_e32 v67, v67, v99
	v_sub_f32_e32 v113, v113, v66
	v_exp_f32_e32 v112, v112
	v_add_f32_e32 v194, v194, v111
	s_waitcnt lgkmcnt(2)
	v_mfma_f32_32x32x16_bf16 v[16:31], v[218:221], v[100:103], v[16:31]
	v_sub_f32_e32 v114, v114, v66
	v_exp_f32_e32 v113, v113
	v_max3_f32 v182, v68, v69, v70
	v_add_f32_e32 v194, v194, v112
	v_sub_f32_e32 v115, v115, v66
	v_exp_f32_e32 v114, v114
	v_add_f32_e32 v194, v194, v113
	v_sub_f32_e32 v116, v116, v66
	v_max3_f32 v182, v182, v71, v72
	v_exp_f32_e32 v115, v115
	v_add_f32_e32 v194, v194, v114
	v_sub_f32_e32 v117, v117, v66
	v_exp_f32_e32 v116, v116
	v_add_f32_e32 v194, v194, v115
	v_max3_f32 v182, v182, v73, v74
	v_cvt_pk_bf16_f32 v108, v108, v109
	v_cvt_pk_bf16_f32 v109, v110, v111
	v_cvt_pk_bf16_f32 v110, v112, v113
	v_cvt_pk_bf16_f32 v111, v114, v115
	ds_read2_b64 v[206:209], v210 offset0:136 offset1:138
	ds_read2_b64 v[218:221], v211 offset0:168 offset1:170
	v_sub_f32_e32 v118, v118, v66
	v_max3_f32 v182, v182, v75, v76
	v_exp_f32_e32 v117, v117
	s_waitcnt lgkmcnt(3)
	v_mfma_f32_32x32x16_bf16 v[48:63], v[202:205], v[108:111], v[48:63]
	v_add_f32_e32 v194, v194, v116
	v_sub_f32_e32 v119, v119, v66
	v_exp_f32_e32 v118, v118
	v_add_f32_e32 v194, v194, v117
	v_max3_f32 v182, v182, v77, v78
	v_sub_f32_e32 v120, v120, v66
	v_exp_f32_e32 v119, v119
	v_add_f32_e32 v194, v194, v118
	v_sub_f32_e32 v121, v121, v66
	v_exp_f32_e32 v120, v120
	v_max3_f32 v182, v182, v79, v80
	v_add_f32_e32 v194, v194, v119
	s_waitcnt lgkmcnt(2)
	v_mfma_f32_32x32x16_bf16 v[16:31], v[104:107], v[108:111], v[16:31]
	v_sub_f32_e32 v122, v122, v66
	v_exp_f32_e32 v121, v121
	v_add_f32_e32 v194, v194, v120
	v_sub_f32_e32 v123, v123, v66
	v_max3_f32 v182, v182, v81, v82
	v_exp_f32_e32 v122, v122
	v_add_f32_e32 v194, v194, v121
	v_sub_f32_e32 v124, v124, v66
	v_exp_f32_e32 v123, v123
	v_add_f32_e32 v194, v194, v122
	v_max_f32_e32 v182, v182, v83
	v_sub_f32_e32 v125, v125, v66
	v_exp_f32_e32 v124, v124
	v_add_f32_e32 v194, v194, v123
	v_cvt_pk_bf16_f32 v116, v116, v117
	v_cvt_pk_bf16_f32 v117, v118, v119
	v_max_f32_e32 v67, v67, v182
	v_cvt_pk_bf16_f32 v118, v120, v121
	v_cvt_pk_bf16_f32 v119, v122, v123
	ds_read2_b64 v[112:115], v210 offset0:140 offset1:142
	ds_read2_b64 v[202:205], v211 offset0:172 offset1:174
	v_sub_f32_e32 v126, v126, v66
	v_exp_f32_e32 v125, v125
	s_waitcnt lgkmcnt(3)
	v_mfma_f32_32x32x16_bf16 v[48:63], v[206:209], v[116:119], v[48:63]
	v_add_f32_e32 v194, v194, v124
	ds_bpermute_b32 v182, v191, v67
	v_sub_f32_e32 v127, v127, v66
	v_exp_f32_e32 v126, v126
	v_add_f32_e32 v194, v194, v125
	v_sub_f32_e32 v128, v128, v66
	v_exp_f32_e32 v127, v127
	v_add_f32_e32 v194, v194, v126
	v_sub_f32_e32 v129, v129, v66
	v_exp_f32_e32 v128, v128
	v_add_f32_e32 v194, v194, v127
	s_waitcnt lgkmcnt(3)
	v_mfma_f32_32x32x16_bf16 v[16:31], v[218:221], v[116:119], v[16:31]
	v_sub_f32_e32 v130, v130, v66
	v_exp_f32_e32 v129, v129
	v_add_f32_e32 v194, v194, v128
	v_sub_f32_e32 v131, v131, v66
	v_exp_f32_e32 v130, v130
	v_add_f32_e32 v194, v194, v129
	v_exp_f32_e32 v131, v131
	v_add_f32_e32 v194, v194, v130
	v_add_f32_e32 v194, v194, v131
	v_cvt_pk_bf16_f32 v124, v124, v125
	v_cvt_pk_bf16_f32 v125, v126, v127
	v_cvt_pk_bf16_f32 v126, v128, v129
	v_cvt_pk_bf16_f32 v127, v130, v131
	ds_read2_b64 v[104:107], v210 offset0:128 offset1:130
	ds_read2_b64 v[120:123], v211 offset0:160 offset1:162
	s_nop 1
	s_waitcnt lgkmcnt(4)
	v_mfma_f32_32x32x16_bf16 v[48:63], v[112:115], v[124:127], v[48:63]
	s_waitcnt lgkmcnt(3)
	v_mfma_f32_32x32x16_bf16 v[16:31], v[202:205], v[124:127], v[16:31]
	s_waitcnt lgkmcnt(2)
	v_max3_f32 v64, v217, v67, v182
	v_cmp_gt_f32_e32 vcc, v64, v217
	s_cbranch_vccz .Lattn_keep1
	v_sub_f32_e32 v182, v217, v64
	v_exp_f32_e32 v182, v182
	s_nop 0
	v_pk_mul_f32 v[32:33], v[32:33], v[182:183] op_sel_hi:[1,0]
	v_pk_mul_f32 v[34:35], v[34:35], v[182:183] op_sel_hi:[1,0]
	v_pk_mul_f32 v[36:37], v[36:37], v[182:183] op_sel_hi:[1,0]
	v_pk_mul_f32 v[38:39], v[38:39], v[182:183] op_sel_hi:[1,0]
	v_pk_mul_f32 v[40:41], v[40:41], v[182:183] op_sel_hi:[1,0]
	v_pk_mul_f32 v[42:43], v[42:43], v[182:183] op_sel_hi:[1,0]
	v_pk_mul_f32 v[44:45], v[44:45], v[182:183] op_sel_hi:[1,0]
	v_pk_mul_f32 v[46:47], v[46:47], v[182:183] op_sel_hi:[1,0]
	v_pk_mul_f32 v[0:1], v[0:1], v[182:183] op_sel_hi:[1,0]
	v_pk_mul_f32 v[2:3], v[2:3], v[182:183] op_sel_hi:[1,0]
	v_pk_mul_f32 v[4:5], v[4:5], v[182:183] op_sel_hi:[1,0]
	v_pk_mul_f32 v[6:7], v[6:7], v[182:183] op_sel_hi:[1,0]
	v_pk_mul_f32 v[8:9], v[8:9], v[182:183] op_sel_hi:[1,0]
	v_pk_mul_f32 v[10:11], v[10:11], v[182:183] op_sel_hi:[1,0]
	v_pk_mul_f32 v[12:13], v[12:13], v[182:183] op_sel_hi:[1,0]
	v_pk_mul_f32 v[14:15], v[14:15], v[182:183] op_sel_hi:[1,0]
	v_mul_f32_e32 v195, v195, v182
.Lattn_keep1:
	v_sub_f32_e32 v84, v84, v64
	v_sub_f32_e32 v85, v85, v64
	v_exp_f32_e32 v84, v84
	v_sub_f32_e32 v86, v86, v64
	v_exp_f32_e32 v85, v85
	v_add_f32_e32 v195, v195, v84
	v_sub_f32_e32 v87, v87, v64
	v_exp_f32_e32 v86, v86
	v_add_f32_e32 v195, v195, v85
	v_sub_f32_e32 v88, v88, v64
	v_exp_f32_e32 v87, v87
	v_add_f32_e32 v195, v195, v86
	v_sub_f32_e32 v89, v89, v64
	v_exp_f32_e32 v88, v88
	v_add_f32_e32 v195, v195, v87
	v_sub_f32_e32 v90, v90, v64
	v_exp_f32_e32 v89, v89
	v_add_f32_e32 v195, v195, v88
	v_sub_f32_e32 v91, v91, v64
	v_exp_f32_e32 v90, v90
	v_add_f32_e32 v195, v195, v89
	v_sub_f32_e32 v92, v92, v64
	v_exp_f32_e32 v91, v91
	v_add_f32_e32 v195, v195, v90
	v_sub_f32_e32 v93, v93, v64
	v_exp_f32_e32 v92, v92
	v_add_f32_e32 v195, v195, v91
	v_cvt_pk_bf16_f32 v84, v84, v85
	v_cvt_pk_bf16_f32 v85, v86, v87
	v_cvt_pk_bf16_f32 v86, v88, v89
	v_cvt_pk_bf16_f32 v87, v90, v91
	ds_read2_b64 v[206:209], v210 offset0:132 offset1:134
	ds_read2_b64 v[218:221], v211 offset0:164 offset1:166
	v_sub_f32_e32 v94, v94, v64
	v_exp_f32_e32 v93, v93
	s_waitcnt lgkmcnt(3)
	v_mfma_f32_32x32x16_bf16 v[32:47], v[104:107], v[84:87], v[32:47]
	v_add_f32_e32 v195, v195, v92
	v_sub_f32_e32 v95, v95, v64
	v_exp_f32_e32 v94, v94
	v_add_f32_e32 v195, v195, v93
	v_sub_f32_e32 v96, v96, v64
	v_exp_f32_e32 v95, v95
	v_add_f32_e32 v195, v195, v94
	v_sub_f32_e32 v97, v97, v64
	v_exp_f32_e32 v96, v96
	v_add_f32_e32 v195, v195, v95
	s_waitcnt lgkmcnt(2)
	v_mfma_f32_32x32x16_bf16 v[0:15], v[120:123], v[84:87], v[0:15]
	v_sub_f32_e32 v98, v98, v64
	v_exp_f32_e32 v97, v97
	v_add_f32_e32 v195, v195, v96
	v_sub_f32_e32 v99, v99, v64
	v_exp_f32_e32 v98, v98
	v_add_f32_e32 v195, v195, v97
	v_sub_f32_e32 v68, v68, v64
	v_exp_f32_e32 v99, v99
	v_add_f32_e32 v195, v195, v98
	v_sub_f32_e32 v69, v69, v64
	v_exp_f32_e32 v68, v68
	v_add_f32_e32 v195, v195, v99
	v_cvt_pk_bf16_f32 v92, v92, v93
	v_cvt_pk_bf16_f32 v93, v94, v95
	v_cvt_pk_bf16_f32 v94, v96, v97
	v_cvt_pk_bf16_f32 v95, v98, v99
	ds_read2_b64 v[128:131], v210 offset0:136 offset1:138
	ds_read2_b64 v[112:115], v211 offset0:168 offset1:170
	v_sub_f32_e32 v70, v70, v64
	v_exp_f32_e32 v69, v69
	s_waitcnt lgkmcnt(3)
	v_mfma_f32_32x32x16_bf16 v[32:47], v[206:209], v[92:95], v[32:47]
	v_add_f32_e32 v195, v195, v68
	v_sub_f32_e32 v71, v71, v64
	v_exp_f32_e32 v70, v70
	v_add_f32_e32 v195, v195, v69
	v_sub_f32_e32 v72, v72, v64
	v_exp_f32_e32 v71, v71
	v_add_f32_e32 v195, v195, v70
	v_sub_f32_e32 v73, v73, v64
	v_exp_f32_e32 v72, v72
	v_add_f32_e32 v195, v195, v71
	s_waitcnt lgkmcnt(2)
	v_mfma_f32_32x32x16_bf16 v[0:15], v[218:221], v[92:95], v[0:15]
	v_sub_f32_e32 v74, v74, v64
	v_exp_f32_e32 v73, v73
	v_add_f32_e32 v195, v195, v72
	v_sub_f32_e32 v75, v75, v64
	v_exp_f32_e32 v74, v74
	v_add_f32_e32 v195, v195, v73
	v_sub_f32_e32 v76, v76, v64
	v_exp_f32_e32 v75, v75
	v_add_f32_e32 v195, v195, v74
	v_sub_f32_e32 v77, v77, v64
	v_exp_f32_e32 v76, v76
	v_add_f32_e32 v195, v195, v75
	v_cvt_pk_bf16_f32 v68, v68, v69
	v_cvt_pk_bf16_f32 v69, v70, v71
	v_cvt_pk_bf16_f32 v70, v72, v73
	v_cvt_pk_bf16_f32 v71, v74, v75
	ds_read2_b64 v[202:205], v210 offset0:140 offset1:142
	ds_read2_b64 v[88:91], v211 offset0:172 offset1:174
	v_sub_f32_e32 v78, v78, v64
	v_exp_f32_e32 v77, v77
	s_waitcnt lgkmcnt(3)
	v_mfma_f32_32x32x16_bf16 v[32:47], v[128:131], v[68:71], v[32:47]
	v_add_f32_e32 v195, v195, v76
	v_sub_f32_e32 v79, v79, v64
	v_exp_f32_e32 v78, v78
	v_add_f32_e32 v195, v195, v77
	v_sub_f32_e32 v80, v80, v64
	v_exp_f32_e32 v79, v79
	v_add_f32_e32 v195, v195, v78
	v_sub_f32_e32 v81, v81, v64
	v_exp_f32_e32 v80, v80
	v_add_f32_e32 v195, v195, v79
	s_waitcnt lgkmcnt(2)
	v_mfma_f32_32x32x16_bf16 v[0:15], v[112:115], v[68:71], v[0:15]
	v_sub_f32_e32 v82, v82, v64
	v_exp_f32_e32 v81, v81
	v_add_f32_e32 v195, v195, v80
	v_sub_f32_e32 v83, v83, v64
	v_exp_f32_e32 v82, v82
	v_add_f32_e32 v195, v195, v81
	v_exp_f32_e32 v83, v83
	v_add_f32_e32 v195, v195, v82
	v_add_f32_e32 v195, v195, v83
	v_cvt_pk_bf16_f32 v76, v76, v77
	v_cvt_pk_bf16_f32 v77, v78, v79
	v_cvt_pk_bf16_f32 v78, v80, v81
	v_cvt_pk_bf16_f32 v79, v82, v83
	s_nop 1
	s_waitcnt lgkmcnt(1)
	v_mfma_f32_32x32x16_bf16 v[32:47], v[202:205], v[76:79], v[32:47]
	s_waitcnt lgkmcnt(0)
	v_mfma_f32_32x32x16_bf16 v[0:15], v[88:91], v[76:79], v[0:15]
	s_bitcmp1_b32 s50, 0
	s_cselect_b32 s0, 0x4600, 0
	s_add_i32 s53, s53, s33
	s_addk_i32 s52, 0x4000
	s_add_i32 s50, s50, 1
	v_lshl_add_u64 v[198:199], v[198:199], 0, s[18:19]
	v_lshl_add_u64 v[200:201], v[200:201], 0, s[20:21]
	s_cmpk_lg_i32 s50, 0x44
	v_add_u32_e32 v67, s0, v192
	v_add_u32_e32 v182, s0, v196
	v_add_u32_e32 v197, 0x2400, v182
	v_add_u32_e32 v182, 0x3500, v182
	s_waitcnt vmcnt(0)
	ds_write_b128 v67, v[136:139]
	ds_write_b128 v67, v[140:143] offset:4608
	ds_write2_b64 v197, v[176:177], v[178:179] offset1:1
	ds_write2_b64 v182, v[144:145], v[146:147] offset1:1
	s_waitcnt lgkmcnt(0)
	s_barrier
	s_cbranch_scc0 .LBB0_460
	v_mov_b32_e32 v217, v64
	v_mov_b32_e32 v216, v66
	s_branch .LBB0_430
